# K-loops: drop redundant setprio 0/1 pair between MFMA blocks and duplicate lgkmcnt(0) after barrier (all 4 GEMMs)
# speedup vs baseline: 1.0092x; 1.0092x over previous
.LBB0_91:
	s_add_u32 s8, s42, 0xfff80080
	s_addc_u32 s9, s43, -1
	s_add_i32 s70, 0, 0x10000
	s_cmp_eq_u32 s69, 28
	s_cselect_b32 vcc_hi, s7, s9
	s_cselect_b32 vcc_lo, s45, s8
	v_add_u32_e32 v1, s70, v169
	s_cselect_b32 s9, s65, s68
	s_cselect_b32 s8, s66, s67
	s_add_i32 s72, 0, 0x14000
	ds_read_b128 v[136:139], v1
	ds_read_b128 v[140:143], v1 offset:1024
	ds_read_b128 v[144:147], v1 offset:2048
	ds_read_b128 v[148:151], v1 offset:3072
	v_add_u32_e32 v1, s72, v169
	ds_read_b128 v[152:155], v1
	ds_read_b128 v[186:189], v1 offset:1024
	ds_read_b128 v[190:193], v1 offset:2048
	ds_read_b128 v[194:197], v1 offset:3072
	v_lshl_add_u64 v[170:171], s[42:43], 0, v[162:163]
	s_add_i32 m0, s97, 0xc000
	ds_read_b128 v[198:201], v214
	ds_read_b128 v[216:219], v214 offset:1024
	ds_read_b128 v[220:223], v214 offset:2048
	ds_read_b128 v[224:227], v214 offset:3072
	ds_read_b128 v[228:231], v214 offset:4096
	ds_read_b128 v[232:235], v214 offset:5120
	ds_read_b128 v[236:239], v214 offset:6144
	ds_read_b128 v[240:243], v214 offset:7168
	global_load_lds_dwordx4 v[170:171], off
	v_lshl_add_u64 v[170:171], s[42:43], 0, v[184:185]
	s_add_i32 m0, s97, 0xe000
	s_nop 0
	global_load_lds_dwordx4 v[170:171], off
	s_waitcnt vmcnt(8)
	s_waitcnt lgkmcnt(0)
	s_barrier
	s_setprio 1
	v_mfma_f32_16x16x32_bf16 v[132:135], v[136:139], v[198:201], v[132:135]
	v_mfma_f32_16x16x32_bf16 v[128:131], v[144:147], v[198:201], v[128:131]
	v_mfma_f32_16x16x32_bf16 v[116:119], v[136:139], v[220:223], v[116:119]
	v_mfma_f32_16x16x32_bf16 v[106:109], v[144:147], v[220:223], v[106:109]
	v_mfma_f32_16x16x32_bf16 v[94:97], v[136:139], v[228:231], v[94:97]
	v_mfma_f32_16x16x32_bf16 v[90:93], v[144:147], v[228:231], v[90:93]
	v_mfma_f32_16x16x32_bf16 v[78:81], v[136:139], v[236:239], v[78:81]
	v_mfma_f32_16x16x32_bf16 v[74:77], v[144:147], v[236:239], v[74:77]
	v_mfma_f32_16x16x32_bf16 v[132:135], v[140:143], v[216:219], v[132:135]
	v_mfma_f32_16x16x32_bf16 v[128:131], v[148:151], v[216:219], v[128:131]
	v_mfma_f32_16x16x32_bf16 v[116:119], v[140:143], v[224:227], v[116:119]
	v_mfma_f32_16x16x32_bf16 v[106:109], v[148:151], v[224:227], v[106:109]
	v_mfma_f32_16x16x32_bf16 v[94:97], v[140:143], v[232:235], v[94:97]
	v_mfma_f32_16x16x32_bf16 v[90:93], v[148:151], v[232:235], v[90:93]
	v_mfma_f32_16x16x32_bf16 v[78:81], v[140:143], v[240:243], v[78:81]
	v_mfma_f32_16x16x32_bf16 v[74:77], v[148:151], v[240:243], v[74:77]
	v_mfma_f32_16x16x32_bf16 v[124:127], v[152:155], v[198:201], v[124:127]
	v_mfma_f32_16x16x32_bf16 v[120:123], v[190:193], v[198:201], v[120:123]
	v_mfma_f32_16x16x32_bf16 v[102:105], v[152:155], v[220:223], v[102:105]
	v_mfma_f32_16x16x32_bf16 v[98:101], v[190:193], v[220:223], v[98:101]
	v_mfma_f32_16x16x32_bf16 v[86:89], v[152:155], v[228:231], v[86:89]
	v_mfma_f32_16x16x32_bf16 v[82:85], v[190:193], v[228:231], v[82:85]
	v_mfma_f32_16x16x32_bf16 v[70:73], v[152:155], v[236:239], v[70:73]
	v_mfma_f32_16x16x32_bf16 v[66:69], v[190:193], v[236:239], v[66:69]
	v_mfma_f32_16x16x32_bf16 v[124:127], v[186:189], v[216:219], v[124:127]
	v_mfma_f32_16x16x32_bf16 v[120:123], v[194:197], v[216:219], v[120:123]
	v_mfma_f32_16x16x32_bf16 v[102:105], v[186:189], v[224:227], v[102:105]
	v_mfma_f32_16x16x32_bf16 v[98:101], v[194:197], v[224:227], v[98:101]
	v_mfma_f32_16x16x32_bf16 v[86:89], v[186:189], v[232:235], v[86:89]
	v_mfma_f32_16x16x32_bf16 v[82:85], v[194:197], v[232:235], v[82:85]
	v_mfma_f32_16x16x32_bf16 v[70:73], v[186:189], v[240:243], v[70:73]
	v_mfma_f32_16x16x32_bf16 v[66:69], v[194:197], v[240:243], v[66:69]
	s_setprio 0
	s_barrier
	s_add_i32 s70, s70, s57
	v_lshl_add_u64 v[170:171], s[8:9], 0, v[156:157]
	s_mov_b32 m0, s70
	ds_read_b128 v[198:201], v214 offset:16384
	ds_read_b128 v[216:219], v214 offset:17408
	ds_read_b128 v[220:223], v214 offset:18432
	ds_read_b128 v[224:227], v214 offset:19456
	ds_read_b128 v[228:231], v214 offset:20480
	ds_read_b128 v[232:235], v214 offset:21504
	ds_read_b128 v[236:239], v214 offset:22528
	ds_read_b128 v[240:243], v214 offset:23552
	global_load_lds_dwordx4 v[170:171], off
	s_add_i32 m0, s70, 0x2000
	s_add_u32 s70, s8, 0x80000
	v_lshl_add_u64 v[172:173], s[8:9], 0, v[160:161]
	s_addc_u32 s71, s9, 0
	s_add_i32 s72, s72, s57
	global_load_lds_dwordx4 v[172:173], off
	v_lshl_add_u64 v[244:245], s[70:71], 0, v[156:157]
	s_mov_b32 m0, s72
	v_lshl_add_u64 v[246:247], vcc, 0, v[158:159]
	global_load_lds_dwordx4 v[244:245], off
	v_lshl_add_u64 v[244:245], s[70:71], 0, v[160:161]
	s_add_i32 m0, s72, 0x2000
	s_nop 0
	global_load_lds_dwordx4 v[244:245], off
	v_lshl_add_u64 v[244:245], vcc, 0, v[110:111]
	s_mov_b32 m0, s97
	s_nop 0
	global_load_lds_dwordx4 v[244:245], off
	s_mov_b32 m0, s35
	s_nop 0
	global_load_lds_dwordx4 v[246:247], off
	s_waitcnt vmcnt(8)
	s_waitcnt lgkmcnt(0)
	s_barrier
	s_setprio 1
	v_mfma_f32_16x16x32_bf16 v[62:65], v[136:139], v[198:201], v[62:65]
	v_mfma_f32_16x16x32_bf16 v[58:61], v[144:147], v[198:201], v[58:61]
	v_mfma_f32_16x16x32_bf16 v[46:49], v[136:139], v[220:223], v[46:49]
	v_mfma_f32_16x16x32_bf16 v[42:45], v[144:147], v[220:223], v[42:45]
	v_mfma_f32_16x16x32_bf16 v[30:33], v[136:139], v[228:231], v[30:33]
	v_mfma_f32_16x16x32_bf16 v[26:29], v[144:147], v[228:231], v[26:29]
	v_mfma_f32_16x16x32_bf16 v[14:17], v[136:139], v[236:239], v[14:17]
	v_mfma_f32_16x16x32_bf16 v[10:13], v[144:147], v[236:239], v[10:13]
	v_mfma_f32_16x16x32_bf16 v[62:65], v[140:143], v[216:219], v[62:65]
	v_mfma_f32_16x16x32_bf16 v[58:61], v[148:151], v[216:219], v[58:61]
	v_mfma_f32_16x16x32_bf16 v[46:49], v[140:143], v[224:227], v[46:49]
	v_mfma_f32_16x16x32_bf16 v[42:45], v[148:151], v[224:227], v[42:45]
	v_mfma_f32_16x16x32_bf16 v[30:33], v[140:143], v[232:235], v[30:33]
	v_mfma_f32_16x16x32_bf16 v[26:29], v[148:151], v[232:235], v[26:29]
	v_mfma_f32_16x16x32_bf16 v[14:17], v[140:143], v[240:243], v[14:17]
	v_mfma_f32_16x16x32_bf16 v[10:13], v[148:151], v[240:243], v[10:13]
	v_mfma_f32_16x16x32_bf16 v[54:57], v[152:155], v[198:201], v[54:57]
	v_mfma_f32_16x16x32_bf16 v[50:53], v[190:193], v[198:201], v[50:53]
	v_mfma_f32_16x16x32_bf16 v[38:41], v[152:155], v[220:223], v[38:41]
	v_mfma_f32_16x16x32_bf16 v[34:37], v[190:193], v[220:223], v[34:37]
	v_mfma_f32_16x16x32_bf16 v[22:25], v[152:155], v[228:231], v[22:25]
	v_mfma_f32_16x16x32_bf16 v[18:21], v[190:193], v[228:231], v[18:21]
	v_mfma_f32_16x16x32_bf16 v[6:9], v[152:155], v[236:239], v[6:9]
	v_mfma_f32_16x16x32_bf16 v[2:5], v[190:193], v[236:239], v[2:5]
	v_mfma_f32_16x16x32_bf16 v[54:57], v[186:189], v[216:219], v[54:57]
	v_mfma_f32_16x16x32_bf16 v[50:53], v[194:197], v[216:219], v[50:53]
	v_mfma_f32_16x16x32_bf16 v[38:41], v[186:189], v[224:227], v[38:41]
	v_mfma_f32_16x16x32_bf16 v[34:37], v[194:197], v[224:227], v[34:37]
	v_mfma_f32_16x16x32_bf16 v[22:25], v[186:189], v[232:235], v[22:25]
	v_mfma_f32_16x16x32_bf16 v[18:21], v[194:197], v[232:235], v[18:21]
	v_mfma_f32_16x16x32_bf16 v[6:9], v[186:189], v[240:243], v[6:9]
	v_mfma_f32_16x16x32_bf16 v[2:5], v[194:197], v[240:243], v[2:5]
	s_setprio 0
	s_barrier
	s_add_i32 s72, 0, 0x18000
	v_add_u32_e32 v1, s72, v169
	s_add_i32 s73, 0, 0x1c000
	ds_read_b128 v[136:139], v1
	ds_read_b128 v[140:143], v1 offset:1024
	ds_read_b128 v[144:147], v1 offset:2048
	ds_read_b128 v[148:151], v1 offset:3072
	v_add_u32_e32 v1, s73, v169
	ds_read_b128 v[152:155], v1
	ds_read_b128 v[186:189], v1 offset:1024
	ds_read_b128 v[190:193], v1 offset:2048
	ds_read_b128 v[194:197], v1 offset:3072
	s_add_u32 s70, vcc_lo, 0x80000
	s_addc_u32 s71, vcc_hi, 0
	s_mov_b32 m0, s55
	v_lshl_add_u64 v[248:249], s[70:71], 0, v[110:111]
	ds_read_b128 v[198:201], v214 offset:32768
	ds_read_b128 v[216:219], v214 offset:33792
	ds_read_b128 v[220:223], v214 offset:34816
	ds_read_b128 v[224:227], v214 offset:35840
	ds_read_b128 v[228:231], v214 offset:36864
	ds_read_b128 v[232:235], v214 offset:37888
	ds_read_b128 v[236:239], v214 offset:38912
	ds_read_b128 v[240:243], v214 offset:39936
	global_load_lds_dwordx4 v[248:249], off
	v_lshl_add_u64 v[248:249], s[70:71], 0, v[158:159]
	s_mov_b32 m0, s34
	s_nop 0
	global_load_lds_dwordx4 v[248:249], off
	s_waitcnt vmcnt(8)
	s_waitcnt lgkmcnt(0)
	s_barrier
	s_setprio 1
	v_mfma_f32_16x16x32_bf16 v[132:135], v[136:139], v[198:201], v[132:135]
	v_mfma_f32_16x16x32_bf16 v[128:131], v[144:147], v[198:201], v[128:131]
	v_mfma_f32_16x16x32_bf16 v[116:119], v[136:139], v[220:223], v[116:119]
	v_mfma_f32_16x16x32_bf16 v[106:109], v[144:147], v[220:223], v[106:109]
	v_mfma_f32_16x16x32_bf16 v[94:97], v[136:139], v[228:231], v[94:97]
	v_mfma_f32_16x16x32_bf16 v[90:93], v[144:147], v[228:231], v[90:93]
	v_mfma_f32_16x16x32_bf16 v[78:81], v[136:139], v[236:239], v[78:81]
	v_mfma_f32_16x16x32_bf16 v[74:77], v[144:147], v[236:239], v[74:77]
	v_mfma_f32_16x16x32_bf16 v[132:135], v[140:143], v[216:219], v[132:135]
	v_mfma_f32_16x16x32_bf16 v[128:131], v[148:151], v[216:219], v[128:131]
	v_mfma_f32_16x16x32_bf16 v[116:119], v[140:143], v[224:227], v[116:119]
	v_mfma_f32_16x16x32_bf16 v[106:109], v[148:151], v[224:227], v[106:109]
	v_mfma_f32_16x16x32_bf16 v[94:97], v[140:143], v[232:235], v[94:97]
	v_mfma_f32_16x16x32_bf16 v[90:93], v[148:151], v[232:235], v[90:93]
	v_mfma_f32_16x16x32_bf16 v[78:81], v[140:143], v[240:243], v[78:81]
	v_mfma_f32_16x16x32_bf16 v[74:77], v[148:151], v[240:243], v[74:77]
	v_mfma_f32_16x16x32_bf16 v[124:127], v[152:155], v[198:201], v[124:127]
	v_mfma_f32_16x16x32_bf16 v[120:123], v[190:193], v[198:201], v[120:123]
	v_mfma_f32_16x16x32_bf16 v[102:105], v[152:155], v[220:223], v[102:105]
	v_mfma_f32_16x16x32_bf16 v[98:101], v[190:193], v[220:223], v[98:101]
	v_mfma_f32_16x16x32_bf16 v[86:89], v[152:155], v[228:231], v[86:89]
	v_mfma_f32_16x16x32_bf16 v[82:85], v[190:193], v[228:231], v[82:85]
	v_mfma_f32_16x16x32_bf16 v[70:73], v[152:155], v[236:239], v[70:73]
	v_mfma_f32_16x16x32_bf16 v[66:69], v[190:193], v[236:239], v[66:69]
	v_mfma_f32_16x16x32_bf16 v[124:127], v[186:189], v[216:219], v[124:127]
	v_mfma_f32_16x16x32_bf16 v[120:123], v[194:197], v[216:219], v[120:123]
	v_mfma_f32_16x16x32_bf16 v[102:105], v[186:189], v[224:227], v[102:105]
	v_mfma_f32_16x16x32_bf16 v[98:101], v[194:197], v[224:227], v[98:101]
	v_mfma_f32_16x16x32_bf16 v[86:89], v[186:189], v[232:235], v[86:89]
	v_mfma_f32_16x16x32_bf16 v[82:85], v[194:197], v[232:235], v[82:85]
	v_mfma_f32_16x16x32_bf16 v[70:73], v[186:189], v[240:243], v[70:73]
	v_mfma_f32_16x16x32_bf16 v[66:69], v[194:197], v[240:243], v[66:69]
	s_setprio 0
	s_barrier
	s_add_i32 s70, s72, s57
	v_lshl_add_u64 v[170:171], v[170:171], 0, s[26:27]
	s_mov_b32 m0, s70
	ds_read_b128 v[198:201], v214 offset:49152
	ds_read_b128 v[216:219], v214 offset:50176
	ds_read_b128 v[220:223], v214 offset:51200
	ds_read_b128 v[224:227], v214 offset:52224
	ds_read_b128 v[228:231], v214 offset:53248
	ds_read_b128 v[232:235], v214 offset:54272
	ds_read_b128 v[236:239], v214 offset:55296
	ds_read_b128 v[240:243], v214 offset:56320
	global_load_lds_dwordx4 v[170:171], off
	s_add_i32 m0, s70, 0x2000
	s_add_u32 s8, s8, 0x80080
	v_lshl_add_u64 v[170:171], v[172:173], 0, s[26:27]
	s_addc_u32 s9, s9, 0
	s_add_i32 s70, s73, s57
	global_load_lds_dwordx4 v[170:171], off
	v_lshl_add_u64 v[170:171], s[8:9], 0, v[156:157]
	s_mov_b32 m0, s70
	s_nop 0
	global_load_lds_dwordx4 v[170:171], off
	v_lshl_add_u64 v[170:171], s[8:9], 0, v[160:161]
	s_add_i32 m0, s70, 0x2000
	s_nop 0
	global_load_lds_dwordx4 v[170:171], off
	v_lshl_add_u64 v[170:171], v[244:245], 0, s[26:27]
	s_mov_b32 m0, s60
	s_nop 0
	global_load_lds_dwordx4 v[170:171], off
	v_lshl_add_u64 v[170:171], v[246:247], 0, s[26:27]
	s_mov_b32 m0, s61
	s_nop 0
	global_load_lds_dwordx4 v[170:171], off
	s_waitcnt vmcnt(8)
	s_waitcnt lgkmcnt(0)
	s_barrier
	s_setprio 1
	v_mfma_f32_16x16x32_bf16 v[62:65], v[136:139], v[198:201], v[62:65]
	v_mfma_f32_16x16x32_bf16 v[58:61], v[144:147], v[198:201], v[58:61]
	v_mfma_f32_16x16x32_bf16 v[46:49], v[136:139], v[220:223], v[46:49]
	v_mfma_f32_16x16x32_bf16 v[42:45], v[144:147], v[220:223], v[42:45]
	v_mfma_f32_16x16x32_bf16 v[30:33], v[136:139], v[228:231], v[30:33]
	v_mfma_f32_16x16x32_bf16 v[26:29], v[144:147], v[228:231], v[26:29]
	v_mfma_f32_16x16x32_bf16 v[14:17], v[136:139], v[236:239], v[14:17]
	v_mfma_f32_16x16x32_bf16 v[10:13], v[144:147], v[236:239], v[10:13]
	v_mfma_f32_16x16x32_bf16 v[62:65], v[140:143], v[216:219], v[62:65]
	v_mfma_f32_16x16x32_bf16 v[58:61], v[148:151], v[216:219], v[58:61]
	v_mfma_f32_16x16x32_bf16 v[46:49], v[140:143], v[224:227], v[46:49]
	v_mfma_f32_16x16x32_bf16 v[42:45], v[148:151], v[224:227], v[42:45]
	v_mfma_f32_16x16x32_bf16 v[30:33], v[140:143], v[232:235], v[30:33]
	v_mfma_f32_16x16x32_bf16 v[26:29], v[148:151], v[232:235], v[26:29]
	v_mfma_f32_16x16x32_bf16 v[14:17], v[140:143], v[240:243], v[14:17]
	v_mfma_f32_16x16x32_bf16 v[10:13], v[148:151], v[240:243], v[10:13]
	v_mfma_f32_16x16x32_bf16 v[54:57], v[152:155], v[198:201], v[54:57]
	v_mfma_f32_16x16x32_bf16 v[50:53], v[190:193], v[198:201], v[50:53]
	v_mfma_f32_16x16x32_bf16 v[38:41], v[152:155], v[220:223], v[38:41]
	v_mfma_f32_16x16x32_bf16 v[34:37], v[190:193], v[220:223], v[34:37]
	v_mfma_f32_16x16x32_bf16 v[22:25], v[152:155], v[228:231], v[22:25]
	v_mfma_f32_16x16x32_bf16 v[18:21], v[190:193], v[228:231], v[18:21]
	v_mfma_f32_16x16x32_bf16 v[6:9], v[152:155], v[236:239], v[6:9]
	v_mfma_f32_16x16x32_bf16 v[2:5], v[190:193], v[236:239], v[2:5]
	v_mfma_f32_16x16x32_bf16 v[54:57], v[186:189], v[216:219], v[54:57]
	v_mfma_f32_16x16x32_bf16 v[50:53], v[194:197], v[216:219], v[50:53]
	v_mfma_f32_16x16x32_bf16 v[38:41], v[186:189], v[224:227], v[38:41]
	v_mfma_f32_16x16x32_bf16 v[34:37], v[194:197], v[224:227], v[34:37]
	v_mfma_f32_16x16x32_bf16 v[22:25], v[186:189], v[232:235], v[22:25]
	v_mfma_f32_16x16x32_bf16 v[18:21], v[194:197], v[232:235], v[18:21]
	v_mfma_f32_16x16x32_bf16 v[6:9], v[186:189], v[240:243], v[6:9]
	v_mfma_f32_16x16x32_bf16 v[2:5], v[194:197], v[240:243], v[2:5]
	s_setprio 0
	s_barrier
	s_add_i32 s69, s69, 2
	s_add_u32 s42, s42, 0x100
	s_addc_u32 s43, s43, 0
	s_add_u32 s67, s67, 0x100
	s_addc_u32 s68, s68, 0
	s_cmp_gt_u32 s69, 29
	s_cbranch_scc0 .LBB0_91
	s_and_b64 vcc, exec, s[16:17]
	s_cbranch_vccz .LBB0_94
	s_barrier

.LBB0_553:
	s_add_i32 s72, s8, 2
	s_add_u32 s9, s92, 0xfff80080
	s_addc_u32 s73, s93, -1
	s_add_i32 s74, 0, 0x10000
	s_cmp_eq_u32 s69, s8
	s_cselect_b32 s95, s7, s73
	s_cselect_b32 s94, s49, s9
	v_add_u32_e32 v154, s74, v1
	s_cselect_b32 s9, s47, s71
	s_cselect_b32 s8, s68, s70
	s_add_i32 s73, 0, 0x14000
	s_waitcnt lgkmcnt(0)
	ds_read_b128 v[150:153], v154
	ds_read_b128 v[158:161], v154 offset:1024
	ds_read_b128 v[184:187], v154 offset:2048
	ds_read_b128 v[188:191], v154 offset:3072
	v_add_u32_e32 v154, s73, v1
	ds_read_b128 v[192:195], v154
	ds_read_b128 v[196:199], v154 offset:1024
	ds_read_b128 v[214:217], v154 offset:2048
	ds_read_b128 v[218:221], v154 offset:3072
	v_lshl_add_u64 v[154:155], s[92:93], 0, v[146:147]
	s_add_i32 m0, s17, 0xc000
	ds_read_b128 v[222:225], v156
	ds_read_b128 v[226:229], v156 offset:1024
	ds_read_b128 v[230:233], v156 offset:2048
	ds_read_b128 v[234:237], v156 offset:3072
	ds_read_b128 v[238:241], v156 offset:4096
	ds_read_b128 v[242:245], v156 offset:5120
	ds_read_b128 v[246:249], v156 offset:6144
	ds_read_b128 v[170:173], v156 offset:7168
	global_load_lds_dwordx4 v[154:155], off
	v_lshl_add_u64 v[154:155], s[92:93], 0, v[148:149]
	s_add_i32 m0, s17, 0xe000
	s_nop 0
	global_load_lds_dwordx4 v[154:155], off
	s_waitcnt vmcnt(8)
	s_waitcnt lgkmcnt(0)
	s_barrier
	s_setprio 1
	v_mfma_f32_16x16x32_bf16 v[132:135], v[150:153], v[222:225], v[132:135]
	v_mfma_f32_16x16x32_bf16 v[128:131], v[184:187], v[222:225], v[128:131]
	v_mfma_f32_16x16x32_bf16 v[124:127], v[150:153], v[230:233], v[124:127]
	v_mfma_f32_16x16x32_bf16 v[120:123], v[184:187], v[230:233], v[120:123]
	v_mfma_f32_16x16x32_bf16 v[106:109], v[150:153], v[238:241], v[106:109]
	v_mfma_f32_16x16x32_bf16 v[98:101], v[184:187], v[238:241], v[98:101]
	v_mfma_f32_16x16x32_bf16 v[90:93], v[150:153], v[246:249], v[90:93]
	v_mfma_f32_16x16x32_bf16 v[82:85], v[184:187], v[246:249], v[82:85]
	v_mfma_f32_16x16x32_bf16 v[132:135], v[158:161], v[226:229], v[132:135]
	v_mfma_f32_16x16x32_bf16 v[128:131], v[188:191], v[226:229], v[128:131]
	v_mfma_f32_16x16x32_bf16 v[124:127], v[158:161], v[234:237], v[124:127]
	v_mfma_f32_16x16x32_bf16 v[120:123], v[188:191], v[234:237], v[120:123]
	v_mfma_f32_16x16x32_bf16 v[106:109], v[158:161], v[242:245], v[106:109]
	v_mfma_f32_16x16x32_bf16 v[98:101], v[188:191], v[242:245], v[98:101]
	v_mfma_f32_16x16x32_bf16 v[90:93], v[158:161], v[170:173], v[90:93]
	v_mfma_f32_16x16x32_bf16 v[82:85], v[188:191], v[170:173], v[82:85]
	v_mfma_f32_16x16x32_bf16 v[116:119], v[192:195], v[222:225], v[116:119]
	v_mfma_f32_16x16x32_bf16 v[102:105], v[214:217], v[222:225], v[102:105]
	v_mfma_f32_16x16x32_bf16 v[94:97], v[192:195], v[230:233], v[94:97]
	v_mfma_f32_16x16x32_bf16 v[86:89], v[214:217], v[230:233], v[86:89]
	v_mfma_f32_16x16x32_bf16 v[78:81], v[192:195], v[238:241], v[78:81]
	v_mfma_f32_16x16x32_bf16 v[74:77], v[214:217], v[238:241], v[74:77]
	v_mfma_f32_16x16x32_bf16 v[70:73], v[192:195], v[246:249], v[70:73]
	v_mfma_f32_16x16x32_bf16 v[66:69], v[214:217], v[246:249], v[66:69]
	v_mfma_f32_16x16x32_bf16 v[116:119], v[196:199], v[226:229], v[116:119]
	v_mfma_f32_16x16x32_bf16 v[102:105], v[218:221], v[226:229], v[102:105]
	v_mfma_f32_16x16x32_bf16 v[94:97], v[196:199], v[234:237], v[94:97]
	v_mfma_f32_16x16x32_bf16 v[86:89], v[218:221], v[234:237], v[86:89]
	v_mfma_f32_16x16x32_bf16 v[78:81], v[196:199], v[242:245], v[78:81]
	v_mfma_f32_16x16x32_bf16 v[74:77], v[218:221], v[242:245], v[74:77]
	v_mfma_f32_16x16x32_bf16 v[70:73], v[196:199], v[170:173], v[70:73]
	v_mfma_f32_16x16x32_bf16 v[66:69], v[218:221], v[170:173], v[66:69]
	s_setprio 0
	s_barrier
	s_add_i32 s74, s74, s54
	v_lshl_add_u64 v[154:155], s[8:9], 0, v[136:137]
	s_mov_b32 m0, s74
	ds_read_b128 v[170:173], v156 offset:16384
	ds_read_b128 v[222:225], v156 offset:17408
	ds_read_b128 v[226:229], v156 offset:18432
	ds_read_b128 v[230:233], v156 offset:19456
	ds_read_b128 v[234:237], v156 offset:20480
	ds_read_b128 v[238:241], v156 offset:21504
	ds_read_b128 v[242:245], v156 offset:22528
	ds_read_b128 v[246:249], v156 offset:23552
	global_load_lds_dwordx4 v[154:155], off
	s_add_i32 m0, s74, 0x2000
	s_add_u32 s74, s8, 0x80000
	v_lshl_add_u64 v[162:163], s[8:9], 0, v[140:141]
	s_addc_u32 s75, s9, 0
	s_add_i32 s73, s73, s54
	global_load_lds_dwordx4 v[162:163], off
	v_lshl_add_u64 v[200:201], s[74:75], 0, v[136:137]
	s_mov_b32 m0, s73
	v_lshl_add_u64 v[250:251], s[94:95], 0, v[138:139]
	global_load_lds_dwordx4 v[200:201], off
	v_lshl_add_u64 v[200:201], s[74:75], 0, v[140:141]
	s_add_i32 m0, s73, 0x2000
	s_nop 0
	global_load_lds_dwordx4 v[200:201], off
	v_lshl_add_u64 v[200:201], s[94:95], 0, v[110:111]
	s_mov_b32 m0, s17
	s_nop 0
	global_load_lds_dwordx4 v[200:201], off
	s_mov_b32 m0, s58
	s_nop 0
	global_load_lds_dwordx4 v[250:251], off
	s_waitcnt vmcnt(8)
	s_waitcnt lgkmcnt(0)
	s_barrier
	s_setprio 1
	v_mfma_f32_16x16x32_bf16 v[62:65], v[150:153], v[170:173], v[62:65]
	v_mfma_f32_16x16x32_bf16 v[58:61], v[184:187], v[170:173], v[58:61]
	v_mfma_f32_16x16x32_bf16 v[54:57], v[150:153], v[226:229], v[54:57]
	v_mfma_f32_16x16x32_bf16 v[50:53], v[184:187], v[226:229], v[50:53]
	v_mfma_f32_16x16x32_bf16 v[42:45], v[150:153], v[234:237], v[42:45]
	v_mfma_f32_16x16x32_bf16 v[34:37], v[184:187], v[234:237], v[34:37]
	v_mfma_f32_16x16x32_bf16 v[26:29], v[150:153], v[242:245], v[26:29]
	v_mfma_f32_16x16x32_bf16 v[18:21], v[184:187], v[242:245], v[18:21]
	v_mfma_f32_16x16x32_bf16 v[62:65], v[158:161], v[222:225], v[62:65]
	v_mfma_f32_16x16x32_bf16 v[58:61], v[188:191], v[222:225], v[58:61]
	v_mfma_f32_16x16x32_bf16 v[54:57], v[158:161], v[230:233], v[54:57]
	v_mfma_f32_16x16x32_bf16 v[50:53], v[188:191], v[230:233], v[50:53]
	v_mfma_f32_16x16x32_bf16 v[42:45], v[158:161], v[238:241], v[42:45]
	v_mfma_f32_16x16x32_bf16 v[34:37], v[188:191], v[238:241], v[34:37]
	v_mfma_f32_16x16x32_bf16 v[26:29], v[158:161], v[246:249], v[26:29]
	v_mfma_f32_16x16x32_bf16 v[18:21], v[188:191], v[246:249], v[18:21]
	v_mfma_f32_16x16x32_bf16 v[46:49], v[192:195], v[170:173], v[46:49]
	v_mfma_f32_16x16x32_bf16 v[38:41], v[214:217], v[170:173], v[38:41]
	v_mfma_f32_16x16x32_bf16 v[30:33], v[192:195], v[226:229], v[30:33]
	v_mfma_f32_16x16x32_bf16 v[22:25], v[214:217], v[226:229], v[22:25]
	v_mfma_f32_16x16x32_bf16 v[14:17], v[192:195], v[234:237], v[14:17]
	v_mfma_f32_16x16x32_bf16 v[10:13], v[214:217], v[234:237], v[10:13]
	v_mfma_f32_16x16x32_bf16 v[6:9], v[192:195], v[242:245], v[6:9]
	v_mfma_f32_16x16x32_bf16 v[2:5], v[214:217], v[242:245], v[2:5]
	v_mfma_f32_16x16x32_bf16 v[46:49], v[196:199], v[222:225], v[46:49]
	v_mfma_f32_16x16x32_bf16 v[38:41], v[218:221], v[222:225], v[38:41]
	v_mfma_f32_16x16x32_bf16 v[30:33], v[196:199], v[230:233], v[30:33]
	v_mfma_f32_16x16x32_bf16 v[22:25], v[218:221], v[230:233], v[22:25]
	v_mfma_f32_16x16x32_bf16 v[14:17], v[196:199], v[238:241], v[14:17]
	v_mfma_f32_16x16x32_bf16 v[10:13], v[218:221], v[238:241], v[10:13]
	v_mfma_f32_16x16x32_bf16 v[6:9], v[196:199], v[246:249], v[6:9]
	v_mfma_f32_16x16x32_bf16 v[2:5], v[218:221], v[246:249], v[2:5]
	s_setprio 0
	s_barrier
	s_add_i32 s73, 0, 0x18000
	v_add_u32_e32 v157, s73, v1
	s_add_i32 s88, 0, 0x1c000
	ds_read_b128 v[150:153], v157
	ds_read_b128 v[158:161], v157 offset:1024
	ds_read_b128 v[170:173], v157 offset:2048
	ds_read_b128 v[184:187], v157 offset:3072
	v_add_u32_e32 v157, s88, v1
	ds_read_b128 v[188:191], v157
	ds_read_b128 v[192:195], v157 offset:1024
	ds_read_b128 v[196:199], v157 offset:2048
	ds_read_b128 v[214:217], v157 offset:3072
	s_add_u32 s74, s94, 0x80000
	s_addc_u32 s75, s95, 0
	s_mov_b32 m0, s59
	v_lshl_add_u64 v[206:207], s[74:75], 0, v[110:111]
	ds_read_b128 v[218:221], v156 offset:32768
	ds_read_b128 v[222:225], v156 offset:33792
	ds_read_b128 v[226:229], v156 offset:34816
	ds_read_b128 v[230:233], v156 offset:35840
	ds_read_b128 v[234:237], v156 offset:36864
	ds_read_b128 v[238:241], v156 offset:37888
	ds_read_b128 v[242:245], v156 offset:38912
	ds_read_b128 v[246:249], v156 offset:39936
	global_load_lds_dwordx4 v[206:207], off
	v_lshl_add_u64 v[206:207], s[74:75], 0, v[138:139]
	s_mov_b32 m0, s60
	s_nop 0
	global_load_lds_dwordx4 v[206:207], off
	s_waitcnt vmcnt(8)
	s_waitcnt lgkmcnt(0)
	s_barrier
	s_setprio 1
	v_mfma_f32_16x16x32_bf16 v[132:135], v[150:153], v[218:221], v[132:135]
	v_mfma_f32_16x16x32_bf16 v[128:131], v[170:173], v[218:221], v[128:131]
	v_mfma_f32_16x16x32_bf16 v[124:127], v[150:153], v[226:229], v[124:127]
	v_mfma_f32_16x16x32_bf16 v[120:123], v[170:173], v[226:229], v[120:123]
	v_mfma_f32_16x16x32_bf16 v[106:109], v[150:153], v[234:237], v[106:109]
	v_mfma_f32_16x16x32_bf16 v[98:101], v[170:173], v[234:237], v[98:101]
	v_mfma_f32_16x16x32_bf16 v[90:93], v[150:153], v[242:245], v[90:93]
	v_mfma_f32_16x16x32_bf16 v[82:85], v[170:173], v[242:245], v[82:85]
	v_mfma_f32_16x16x32_bf16 v[132:135], v[158:161], v[222:225], v[132:135]
	v_mfma_f32_16x16x32_bf16 v[128:131], v[184:187], v[222:225], v[128:131]
	v_mfma_f32_16x16x32_bf16 v[124:127], v[158:161], v[230:233], v[124:127]
	v_mfma_f32_16x16x32_bf16 v[120:123], v[184:187], v[230:233], v[120:123]
	v_mfma_f32_16x16x32_bf16 v[106:109], v[158:161], v[238:241], v[106:109]
	v_mfma_f32_16x16x32_bf16 v[98:101], v[184:187], v[238:241], v[98:101]
	v_mfma_f32_16x16x32_bf16 v[90:93], v[158:161], v[246:249], v[90:93]
	v_mfma_f32_16x16x32_bf16 v[82:85], v[184:187], v[246:249], v[82:85]
	v_mfma_f32_16x16x32_bf16 v[116:119], v[188:191], v[218:221], v[116:119]
	v_mfma_f32_16x16x32_bf16 v[102:105], v[196:199], v[218:221], v[102:105]
	v_mfma_f32_16x16x32_bf16 v[94:97], v[188:191], v[226:229], v[94:97]
	v_mfma_f32_16x16x32_bf16 v[86:89], v[196:199], v[226:229], v[86:89]
	v_mfma_f32_16x16x32_bf16 v[78:81], v[188:191], v[234:237], v[78:81]
	v_mfma_f32_16x16x32_bf16 v[74:77], v[196:199], v[234:237], v[74:77]
	v_mfma_f32_16x16x32_bf16 v[70:73], v[188:191], v[242:245], v[70:73]
	v_mfma_f32_16x16x32_bf16 v[66:69], v[196:199], v[242:245], v[66:69]
	v_mfma_f32_16x16x32_bf16 v[116:119], v[192:195], v[222:225], v[116:119]
	v_mfma_f32_16x16x32_bf16 v[102:105], v[214:217], v[222:225], v[102:105]
	v_mfma_f32_16x16x32_bf16 v[94:97], v[192:195], v[230:233], v[94:97]
	v_mfma_f32_16x16x32_bf16 v[86:89], v[214:217], v[230:233], v[86:89]
	v_mfma_f32_16x16x32_bf16 v[78:81], v[192:195], v[238:241], v[78:81]
	v_mfma_f32_16x16x32_bf16 v[74:77], v[214:217], v[238:241], v[74:77]
	v_mfma_f32_16x16x32_bf16 v[70:73], v[192:195], v[246:249], v[70:73]
	v_mfma_f32_16x16x32_bf16 v[66:69], v[214:217], v[246:249], v[66:69]
	s_setprio 0
	s_barrier
	s_add_i32 s73, s73, s54
	v_lshl_add_u64 v[154:155], v[154:155], 0, s[26:27]
	s_mov_b32 m0, s73
	ds_read_b128 v[218:221], v156 offset:49152
	ds_read_b128 v[222:225], v156 offset:50176
	ds_read_b128 v[226:229], v156 offset:51200
	ds_read_b128 v[230:233], v156 offset:52224
	ds_read_b128 v[234:237], v156 offset:53248
	ds_read_b128 v[238:241], v156 offset:54272
	ds_read_b128 v[242:245], v156 offset:55296
	ds_read_b128 v[246:249], v156 offset:56320
	global_load_lds_dwordx4 v[154:155], off
	s_add_i32 m0, s73, 0x2000
	s_add_u32 s8, s8, 0x80080
	v_lshl_add_u64 v[154:155], v[162:163], 0, s[26:27]
	s_addc_u32 s9, s9, 0
	s_add_i32 s73, s88, s54
	global_load_lds_dwordx4 v[154:155], off
	v_lshl_add_u64 v[154:155], s[8:9], 0, v[136:137]
	s_mov_b32 m0, s73
	s_nop 0
	global_load_lds_dwordx4 v[154:155], off
	v_lshl_add_u64 v[154:155], s[8:9], 0, v[140:141]
	s_add_i32 m0, s73, 0x2000
	s_nop 0
	global_load_lds_dwordx4 v[154:155], off
	v_lshl_add_u64 v[154:155], v[200:201], 0, s[26:27]
	s_mov_b32 m0, s62
	s_nop 0
	global_load_lds_dwordx4 v[154:155], off
	v_lshl_add_u64 v[154:155], v[250:251], 0, s[26:27]
	s_mov_b32 m0, s63
	s_nop 0
	global_load_lds_dwordx4 v[154:155], off
	s_waitcnt vmcnt(8)
	s_waitcnt lgkmcnt(0)
	s_barrier
	s_setprio 1
	v_mfma_f32_16x16x32_bf16 v[62:65], v[150:153], v[218:221], v[62:65]
	v_mfma_f32_16x16x32_bf16 v[58:61], v[170:173], v[218:221], v[58:61]
	v_mfma_f32_16x16x32_bf16 v[54:57], v[150:153], v[226:229], v[54:57]
	v_mfma_f32_16x16x32_bf16 v[50:53], v[170:173], v[226:229], v[50:53]
	v_mfma_f32_16x16x32_bf16 v[42:45], v[150:153], v[234:237], v[42:45]
	v_mfma_f32_16x16x32_bf16 v[34:37], v[170:173], v[234:237], v[34:37]
	v_mfma_f32_16x16x32_bf16 v[26:29], v[150:153], v[242:245], v[26:29]
	v_mfma_f32_16x16x32_bf16 v[18:21], v[170:173], v[242:245], v[18:21]
	v_mfma_f32_16x16x32_bf16 v[62:65], v[158:161], v[222:225], v[62:65]
	v_mfma_f32_16x16x32_bf16 v[58:61], v[184:187], v[222:225], v[58:61]
	v_mfma_f32_16x16x32_bf16 v[54:57], v[158:161], v[230:233], v[54:57]
	v_mfma_f32_16x16x32_bf16 v[50:53], v[184:187], v[230:233], v[50:53]
	v_mfma_f32_16x16x32_bf16 v[42:45], v[158:161], v[238:241], v[42:45]
	v_mfma_f32_16x16x32_bf16 v[34:37], v[184:187], v[238:241], v[34:37]
	v_mfma_f32_16x16x32_bf16 v[26:29], v[158:161], v[246:249], v[26:29]
	v_mfma_f32_16x16x32_bf16 v[18:21], v[184:187], v[246:249], v[18:21]
	v_mfma_f32_16x16x32_bf16 v[46:49], v[188:191], v[218:221], v[46:49]
	v_mfma_f32_16x16x32_bf16 v[38:41], v[196:199], v[218:221], v[38:41]
	v_mfma_f32_16x16x32_bf16 v[30:33], v[188:191], v[226:229], v[30:33]
	v_mfma_f32_16x16x32_bf16 v[22:25], v[196:199], v[226:229], v[22:25]
	v_mfma_f32_16x16x32_bf16 v[14:17], v[188:191], v[234:237], v[14:17]
	v_mfma_f32_16x16x32_bf16 v[10:13], v[196:199], v[234:237], v[10:13]
	v_mfma_f32_16x16x32_bf16 v[6:9], v[188:191], v[242:245], v[6:9]
	v_mfma_f32_16x16x32_bf16 v[2:5], v[196:199], v[242:245], v[2:5]
	v_mfma_f32_16x16x32_bf16 v[46:49], v[192:195], v[222:225], v[46:49]
	v_mfma_f32_16x16x32_bf16 v[38:41], v[214:217], v[222:225], v[38:41]
	v_mfma_f32_16x16x32_bf16 v[30:33], v[192:195], v[230:233], v[30:33]
	v_mfma_f32_16x16x32_bf16 v[22:25], v[214:217], v[230:233], v[22:25]
	v_mfma_f32_16x16x32_bf16 v[14:17], v[192:195], v[238:241], v[14:17]
	v_mfma_f32_16x16x32_bf16 v[10:13], v[214:217], v[238:241], v[10:13]
	v_mfma_f32_16x16x32_bf16 v[6:9], v[192:195], v[246:249], v[6:9]
	v_mfma_f32_16x16x32_bf16 v[2:5], v[214:217], v[246:249], v[2:5]
	s_setprio 0
	s_barrier
	s_add_u32 s92, s92, 0x100
	s_addc_u32 s93, s93, 0
	s_add_u32 s70, s70, 0x100
	s_addc_u32 s71, s71, 0
	s_cmp_ge_u32 s72, s67
	s_mov_b32 s8, s72
	s_cbranch_scc0 .LBB0_553
	s_and_b64 vcc, exec, s[44:45]
	s_cbranch_vccnz .LBB0_558
	s_cmp_lt_i32 s57, 0
	s_mov_b64 s[8:9], -1
	s_movk_i32 s94, 0x1fff
	s_cbranch_scc1 .LBB0_559

.LBB0_708:
	s_add_u32 s8, s86, 0xfff80080
	s_addc_u32 s9, s87, -1
	s_add_i32 s67, 0, 0x10000
	s_cmp_eq_u32 s66, 28
	s_cselect_b32 s93, s41, s9
	s_cselect_b32 s92, s45, s8
	v_add_u32_e32 v150, s67, v152
	s_cselect_b32 s9, s43, s65
	s_cselect_b32 s8, s63, s64
	s_add_i32 s70, 0, 0x14000
	ds_read_b128 v[146:149], v150
	ds_read_b128 v[156:159], v150 offset:1024
	ds_read_b128 v[160:163], v150 offset:2048
	ds_read_b128 v[170:173], v150 offset:3072
	v_add_u32_e32 v150, s70, v152
	ds_read_b128 v[184:187], v150
	ds_read_b128 v[188:191], v150 offset:1024
	ds_read_b128 v[192:195], v150 offset:2048
	ds_read_b128 v[196:199], v150 offset:3072
	v_lshl_add_u64 v[150:151], s[86:87], 0, v[142:143]
	s_add_i32 m0, s57, 0xc000
	ds_read_b128 v[214:217], v154
	ds_read_b128 v[218:221], v154 offset:1024
	ds_read_b128 v[222:225], v154 offset:2048
	ds_read_b128 v[226:229], v154 offset:3072
	ds_read_b128 v[230:233], v154 offset:4096
	ds_read_b128 v[234:237], v154 offset:5120
	ds_read_b128 v[238:241], v154 offset:6144
	ds_read_b128 v[242:245], v154 offset:7168
	global_load_lds_dwordx4 v[150:151], off
	v_lshl_add_u64 v[150:151], s[86:87], 0, v[144:145]
	s_add_i32 m0, s57, 0xe000
	s_nop 0
	global_load_lds_dwordx4 v[150:151], off
	s_waitcnt vmcnt(8)
	s_waitcnt lgkmcnt(0)
	s_barrier
	s_setprio 1
	v_mfma_f32_16x16x32_bf16 v[132:135], v[146:149], v[214:217], v[132:135]
	v_mfma_f32_16x16x32_bf16 v[128:131], v[160:163], v[214:217], v[128:131]
	v_mfma_f32_16x16x32_bf16 v[116:119], v[146:149], v[222:225], v[116:119]
	v_mfma_f32_16x16x32_bf16 v[106:109], v[160:163], v[222:225], v[106:109]
	v_mfma_f32_16x16x32_bf16 v[94:97], v[146:149], v[230:233], v[94:97]
	v_mfma_f32_16x16x32_bf16 v[90:93], v[160:163], v[230:233], v[90:93]
	v_mfma_f32_16x16x32_bf16 v[78:81], v[146:149], v[238:241], v[78:81]
	v_mfma_f32_16x16x32_bf16 v[74:77], v[160:163], v[238:241], v[74:77]
	v_mfma_f32_16x16x32_bf16 v[132:135], v[156:159], v[218:221], v[132:135]
	v_mfma_f32_16x16x32_bf16 v[128:131], v[170:173], v[218:221], v[128:131]
	v_mfma_f32_16x16x32_bf16 v[116:119], v[156:159], v[226:229], v[116:119]
	v_mfma_f32_16x16x32_bf16 v[106:109], v[170:173], v[226:229], v[106:109]
	v_mfma_f32_16x16x32_bf16 v[94:97], v[156:159], v[234:237], v[94:97]
	v_mfma_f32_16x16x32_bf16 v[90:93], v[170:173], v[234:237], v[90:93]
	v_mfma_f32_16x16x32_bf16 v[78:81], v[156:159], v[242:245], v[78:81]
	v_mfma_f32_16x16x32_bf16 v[74:77], v[170:173], v[242:245], v[74:77]
	v_mfma_f32_16x16x32_bf16 v[124:127], v[184:187], v[214:217], v[124:127]
	v_mfma_f32_16x16x32_bf16 v[120:123], v[192:195], v[214:217], v[120:123]
	v_mfma_f32_16x16x32_bf16 v[102:105], v[184:187], v[222:225], v[102:105]
	v_mfma_f32_16x16x32_bf16 v[98:101], v[192:195], v[222:225], v[98:101]
	v_mfma_f32_16x16x32_bf16 v[86:89], v[184:187], v[230:233], v[86:89]
	v_mfma_f32_16x16x32_bf16 v[82:85], v[192:195], v[230:233], v[82:85]
	v_mfma_f32_16x16x32_bf16 v[70:73], v[184:187], v[238:241], v[70:73]
	v_mfma_f32_16x16x32_bf16 v[66:69], v[192:195], v[238:241], v[66:69]
	v_mfma_f32_16x16x32_bf16 v[124:127], v[188:191], v[218:221], v[124:127]
	v_mfma_f32_16x16x32_bf16 v[120:123], v[196:199], v[218:221], v[120:123]
	v_mfma_f32_16x16x32_bf16 v[102:105], v[188:191], v[226:229], v[102:105]
	v_mfma_f32_16x16x32_bf16 v[98:101], v[196:199], v[226:229], v[98:101]
	v_mfma_f32_16x16x32_bf16 v[86:89], v[188:191], v[234:237], v[86:89]
	v_mfma_f32_16x16x32_bf16 v[82:85], v[196:199], v[234:237], v[82:85]
	v_mfma_f32_16x16x32_bf16 v[70:73], v[188:191], v[242:245], v[70:73]
	v_mfma_f32_16x16x32_bf16 v[66:69], v[196:199], v[242:245], v[66:69]
	s_setprio 0
	s_barrier
	s_add_i32 s67, s67, s54
	v_lshl_add_u64 v[150:151], s[8:9], 0, v[136:137]
	s_mov_b32 m0, s67
	ds_read_b128 v[214:217], v154 offset:16384
	ds_read_b128 v[218:221], v154 offset:17408
	ds_read_b128 v[222:225], v154 offset:18432
	ds_read_b128 v[226:229], v154 offset:19456
	ds_read_b128 v[230:233], v154 offset:20480
	ds_read_b128 v[234:237], v154 offset:21504
	ds_read_b128 v[238:241], v154 offset:22528
	ds_read_b128 v[242:245], v154 offset:23552
	global_load_lds_dwordx4 v[150:151], off
	s_add_i32 m0, s67, 0x2000
	s_add_u32 s68, s8, 0x80000
	v_lshl_add_u64 v[200:201], s[8:9], 0, v[140:141]
	s_addc_u32 s69, s9, 0
	s_add_i32 s67, s70, s54
	global_load_lds_dwordx4 v[200:201], off
	v_lshl_add_u64 v[206:207], s[68:69], 0, v[136:137]
	s_mov_b32 m0, s67
	v_lshl_add_u64 v[246:247], s[92:93], 0, v[138:139]
	global_load_lds_dwordx4 v[206:207], off
	v_lshl_add_u64 v[206:207], s[68:69], 0, v[140:141]
	s_add_i32 m0, s67, 0x2000
	s_nop 0
	global_load_lds_dwordx4 v[206:207], off
	v_lshl_add_u64 v[206:207], s[92:93], 0, v[110:111]
	s_mov_b32 m0, s57
	s_nop 0
	global_load_lds_dwordx4 v[206:207], off
	s_mov_b32 m0, s58
	s_nop 0
	global_load_lds_dwordx4 v[246:247], off
	s_waitcnt vmcnt(8)
	s_waitcnt lgkmcnt(0)
	s_barrier
	s_setprio 1
	v_mfma_f32_16x16x32_bf16 v[62:65], v[146:149], v[214:217], v[62:65]
	v_mfma_f32_16x16x32_bf16 v[58:61], v[160:163], v[214:217], v[58:61]
	v_mfma_f32_16x16x32_bf16 v[46:49], v[146:149], v[222:225], v[46:49]
	v_mfma_f32_16x16x32_bf16 v[42:45], v[160:163], v[222:225], v[42:45]
	v_mfma_f32_16x16x32_bf16 v[30:33], v[146:149], v[230:233], v[30:33]
	v_mfma_f32_16x16x32_bf16 v[26:29], v[160:163], v[230:233], v[26:29]
	v_mfma_f32_16x16x32_bf16 v[14:17], v[146:149], v[238:241], v[14:17]
	v_mfma_f32_16x16x32_bf16 v[10:13], v[160:163], v[238:241], v[10:13]
	v_mfma_f32_16x16x32_bf16 v[62:65], v[156:159], v[218:221], v[62:65]
	v_mfma_f32_16x16x32_bf16 v[58:61], v[170:173], v[218:221], v[58:61]
	v_mfma_f32_16x16x32_bf16 v[46:49], v[156:159], v[226:229], v[46:49]
	v_mfma_f32_16x16x32_bf16 v[42:45], v[170:173], v[226:229], v[42:45]
	v_mfma_f32_16x16x32_bf16 v[30:33], v[156:159], v[234:237], v[30:33]
	v_mfma_f32_16x16x32_bf16 v[26:29], v[170:173], v[234:237], v[26:29]
	v_mfma_f32_16x16x32_bf16 v[14:17], v[156:159], v[242:245], v[14:17]
	v_mfma_f32_16x16x32_bf16 v[10:13], v[170:173], v[242:245], v[10:13]
	v_mfma_f32_16x16x32_bf16 v[54:57], v[184:187], v[214:217], v[54:57]
	v_mfma_f32_16x16x32_bf16 v[50:53], v[192:195], v[214:217], v[50:53]
	v_mfma_f32_16x16x32_bf16 v[38:41], v[184:187], v[222:225], v[38:41]
	v_mfma_f32_16x16x32_bf16 v[34:37], v[192:195], v[222:225], v[34:37]
	v_mfma_f32_16x16x32_bf16 v[22:25], v[184:187], v[230:233], v[22:25]
	v_mfma_f32_16x16x32_bf16 v[18:21], v[192:195], v[230:233], v[18:21]
	v_mfma_f32_16x16x32_bf16 v[6:9], v[184:187], v[238:241], v[6:9]
	v_mfma_f32_16x16x32_bf16 v[2:5], v[192:195], v[238:241], v[2:5]
	v_mfma_f32_16x16x32_bf16 v[54:57], v[188:191], v[218:221], v[54:57]
	v_mfma_f32_16x16x32_bf16 v[50:53], v[196:199], v[218:221], v[50:53]
	v_mfma_f32_16x16x32_bf16 v[38:41], v[188:191], v[226:229], v[38:41]
	v_mfma_f32_16x16x32_bf16 v[34:37], v[196:199], v[226:229], v[34:37]
	v_mfma_f32_16x16x32_bf16 v[22:25], v[188:191], v[234:237], v[22:25]
	v_mfma_f32_16x16x32_bf16 v[18:21], v[196:199], v[234:237], v[18:21]
	v_mfma_f32_16x16x32_bf16 v[6:9], v[188:191], v[242:245], v[6:9]
	v_mfma_f32_16x16x32_bf16 v[2:5], v[196:199], v[242:245], v[2:5]
	s_setprio 0
	s_barrier
	s_add_i32 s67, 0, 0x18000
	v_add_u32_e32 v155, s67, v152
	s_add_i32 s70, 0, 0x1c000
	ds_read_b128 v[146:149], v155
	ds_read_b128 v[156:159], v155 offset:1024
	ds_read_b128 v[160:163], v155 offset:2048
	ds_read_b128 v[170:173], v155 offset:3072
	v_add_u32_e32 v155, s70, v152
	ds_read_b128 v[184:187], v155
	ds_read_b128 v[188:191], v155 offset:1024
	ds_read_b128 v[192:195], v155 offset:2048
	ds_read_b128 v[196:199], v155 offset:3072
	s_add_u32 s68, s92, 0x80000
	s_addc_u32 s69, s93, 0
	s_mov_b32 m0, s59
	v_lshl_add_u64 v[248:249], s[68:69], 0, v[110:111]
	ds_read_b128 v[214:217], v154 offset:32768
	ds_read_b128 v[218:221], v154 offset:33792
	ds_read_b128 v[222:225], v154 offset:34816
	ds_read_b128 v[226:229], v154 offset:35840
	ds_read_b128 v[230:233], v154 offset:36864
	ds_read_b128 v[234:237], v154 offset:37888
	ds_read_b128 v[238:241], v154 offset:38912
	ds_read_b128 v[242:245], v154 offset:39936
	global_load_lds_dwordx4 v[248:249], off
	v_lshl_add_u64 v[248:249], s[68:69], 0, v[138:139]
	s_mov_b32 m0, s60
	s_nop 0
	global_load_lds_dwordx4 v[248:249], off
	s_waitcnt vmcnt(8)
	s_waitcnt lgkmcnt(0)
	s_barrier
	s_setprio 1
	v_mfma_f32_16x16x32_bf16 v[132:135], v[146:149], v[214:217], v[132:135]
	v_mfma_f32_16x16x32_bf16 v[128:131], v[160:163], v[214:217], v[128:131]
	v_mfma_f32_16x16x32_bf16 v[116:119], v[146:149], v[222:225], v[116:119]
	v_mfma_f32_16x16x32_bf16 v[106:109], v[160:163], v[222:225], v[106:109]
	v_mfma_f32_16x16x32_bf16 v[94:97], v[146:149], v[230:233], v[94:97]
	v_mfma_f32_16x16x32_bf16 v[90:93], v[160:163], v[230:233], v[90:93]
	v_mfma_f32_16x16x32_bf16 v[78:81], v[146:149], v[238:241], v[78:81]
	v_mfma_f32_16x16x32_bf16 v[74:77], v[160:163], v[238:241], v[74:77]
	v_mfma_f32_16x16x32_bf16 v[132:135], v[156:159], v[218:221], v[132:135]
	v_mfma_f32_16x16x32_bf16 v[128:131], v[170:173], v[218:221], v[128:131]
	v_mfma_f32_16x16x32_bf16 v[116:119], v[156:159], v[226:229], v[116:119]
	v_mfma_f32_16x16x32_bf16 v[106:109], v[170:173], v[226:229], v[106:109]
	v_mfma_f32_16x16x32_bf16 v[94:97], v[156:159], v[234:237], v[94:97]
	v_mfma_f32_16x16x32_bf16 v[90:93], v[170:173], v[234:237], v[90:93]
	v_mfma_f32_16x16x32_bf16 v[78:81], v[156:159], v[242:245], v[78:81]
	v_mfma_f32_16x16x32_bf16 v[74:77], v[170:173], v[242:245], v[74:77]
	v_mfma_f32_16x16x32_bf16 v[124:127], v[184:187], v[214:217], v[124:127]
	v_mfma_f32_16x16x32_bf16 v[120:123], v[192:195], v[214:217], v[120:123]
	v_mfma_f32_16x16x32_bf16 v[102:105], v[184:187], v[222:225], v[102:105]
	v_mfma_f32_16x16x32_bf16 v[98:101], v[192:195], v[222:225], v[98:101]
	v_mfma_f32_16x16x32_bf16 v[86:89], v[184:187], v[230:233], v[86:89]
	v_mfma_f32_16x16x32_bf16 v[82:85], v[192:195], v[230:233], v[82:85]
	v_mfma_f32_16x16x32_bf16 v[70:73], v[184:187], v[238:241], v[70:73]
	v_mfma_f32_16x16x32_bf16 v[66:69], v[192:195], v[238:241], v[66:69]
	v_mfma_f32_16x16x32_bf16 v[124:127], v[188:191], v[218:221], v[124:127]
	v_mfma_f32_16x16x32_bf16 v[120:123], v[196:199], v[218:221], v[120:123]
	v_mfma_f32_16x16x32_bf16 v[102:105], v[188:191], v[226:229], v[102:105]
	v_mfma_f32_16x16x32_bf16 v[98:101], v[196:199], v[226:229], v[98:101]
	v_mfma_f32_16x16x32_bf16 v[86:89], v[188:191], v[234:237], v[86:89]
	v_mfma_f32_16x16x32_bf16 v[82:85], v[196:199], v[234:237], v[82:85]
	v_mfma_f32_16x16x32_bf16 v[70:73], v[188:191], v[242:245], v[70:73]
	v_mfma_f32_16x16x32_bf16 v[66:69], v[196:199], v[242:245], v[66:69]
	s_setprio 0
	s_barrier
	s_add_i32 s67, s67, s54
	v_lshl_add_u64 v[150:151], v[150:151], 0, s[26:27]
	s_mov_b32 m0, s67
	ds_read_b128 v[214:217], v154 offset:49152
	ds_read_b128 v[218:221], v154 offset:50176
	ds_read_b128 v[222:225], v154 offset:51200
	ds_read_b128 v[226:229], v154 offset:52224
	ds_read_b128 v[230:233], v154 offset:53248
	ds_read_b128 v[234:237], v154 offset:54272
	ds_read_b128 v[238:241], v154 offset:55296
	ds_read_b128 v[242:245], v154 offset:56320
	global_load_lds_dwordx4 v[150:151], off
	s_add_i32 m0, s67, 0x2000
	s_add_u32 s8, s8, 0x80080
	v_lshl_add_u64 v[150:151], v[200:201], 0, s[26:27]
	s_addc_u32 s9, s9, 0
	s_add_i32 s67, s70, s54
	global_load_lds_dwordx4 v[150:151], off
	v_lshl_add_u64 v[150:151], s[8:9], 0, v[136:137]
	s_mov_b32 m0, s67
	s_nop 0
	global_load_lds_dwordx4 v[150:151], off
	v_lshl_add_u64 v[150:151], s[8:9], 0, v[140:141]
	s_add_i32 m0, s67, 0x2000
	s_nop 0
	global_load_lds_dwordx4 v[150:151], off
	v_lshl_add_u64 v[150:151], v[206:207], 0, s[26:27]
	s_mov_b32 m0, s37
	s_nop 0
	global_load_lds_dwordx4 v[150:151], off
	v_lshl_add_u64 v[150:151], v[246:247], 0, s[26:27]
	s_mov_b32 m0, s61
	s_nop 0
	global_load_lds_dwordx4 v[150:151], off
	s_waitcnt vmcnt(8)
	s_waitcnt lgkmcnt(0)
	s_barrier
	s_setprio 1
	v_mfma_f32_16x16x32_bf16 v[62:65], v[146:149], v[214:217], v[62:65]
	v_mfma_f32_16x16x32_bf16 v[58:61], v[160:163], v[214:217], v[58:61]
	v_mfma_f32_16x16x32_bf16 v[46:49], v[146:149], v[222:225], v[46:49]
	v_mfma_f32_16x16x32_bf16 v[42:45], v[160:163], v[222:225], v[42:45]
	v_mfma_f32_16x16x32_bf16 v[30:33], v[146:149], v[230:233], v[30:33]
	v_mfma_f32_16x16x32_bf16 v[26:29], v[160:163], v[230:233], v[26:29]
	v_mfma_f32_16x16x32_bf16 v[14:17], v[146:149], v[238:241], v[14:17]
	v_mfma_f32_16x16x32_bf16 v[10:13], v[160:163], v[238:241], v[10:13]
	v_mfma_f32_16x16x32_bf16 v[62:65], v[156:159], v[218:221], v[62:65]
	v_mfma_f32_16x16x32_bf16 v[58:61], v[170:173], v[218:221], v[58:61]
	v_mfma_f32_16x16x32_bf16 v[46:49], v[156:159], v[226:229], v[46:49]
	v_mfma_f32_16x16x32_bf16 v[42:45], v[170:173], v[226:229], v[42:45]
	v_mfma_f32_16x16x32_bf16 v[30:33], v[156:159], v[234:237], v[30:33]
	v_mfma_f32_16x16x32_bf16 v[26:29], v[170:173], v[234:237], v[26:29]
	v_mfma_f32_16x16x32_bf16 v[14:17], v[156:159], v[242:245], v[14:17]
	v_mfma_f32_16x16x32_bf16 v[10:13], v[170:173], v[242:245], v[10:13]
	v_mfma_f32_16x16x32_bf16 v[54:57], v[184:187], v[214:217], v[54:57]
	v_mfma_f32_16x16x32_bf16 v[50:53], v[192:195], v[214:217], v[50:53]
	v_mfma_f32_16x16x32_bf16 v[38:41], v[184:187], v[222:225], v[38:41]
	v_mfma_f32_16x16x32_bf16 v[34:37], v[192:195], v[222:225], v[34:37]
	v_mfma_f32_16x16x32_bf16 v[22:25], v[184:187], v[230:233], v[22:25]
	v_mfma_f32_16x16x32_bf16 v[18:21], v[192:195], v[230:233], v[18:21]
	v_mfma_f32_16x16x32_bf16 v[6:9], v[184:187], v[238:241], v[6:9]
	v_mfma_f32_16x16x32_bf16 v[2:5], v[192:195], v[238:241], v[2:5]
	v_mfma_f32_16x16x32_bf16 v[54:57], v[188:191], v[218:221], v[54:57]
	v_mfma_f32_16x16x32_bf16 v[50:53], v[196:199], v[218:221], v[50:53]
	v_mfma_f32_16x16x32_bf16 v[38:41], v[188:191], v[226:229], v[38:41]
	v_mfma_f32_16x16x32_bf16 v[34:37], v[196:199], v[226:229], v[34:37]
	v_mfma_f32_16x16x32_bf16 v[22:25], v[188:191], v[234:237], v[22:25]
	v_mfma_f32_16x16x32_bf16 v[18:21], v[196:199], v[234:237], v[18:21]
	v_mfma_f32_16x16x32_bf16 v[6:9], v[188:191], v[242:245], v[6:9]
	v_mfma_f32_16x16x32_bf16 v[2:5], v[196:199], v[242:245], v[2:5]
	s_setprio 0
	s_barrier
	s_add_i32 s66, s66, 2
	s_add_u32 s86, s86, 0x100
	s_addc_u32 s87, s87, 0
	s_add_u32 s64, s64, 0x100
	s_addc_u32 s65, s65, 0
	s_cmp_gt_u32 s66, 29
	s_cbranch_scc0 .LBB0_708
	s_and_b64 vcc, exec, s[16:17]
	s_cbranch_vccz .LBB0_711
	s_barrier

.LBB0_853:
	s_add_i32 s71, s8, 2
	s_add_u32 s9, s86, 0xffe00080
	s_addc_u32 s72, s87, -1
	s_add_i32 s73, 0, 0x10000
	s_cmp_eq_u32 s68, s8
	s_cselect_b32 s93, s7, s72
	s_cselect_b32 s92, s47, s9
	v_add_u32_e32 v154, s73, v1
	s_cselect_b32 s9, s45, s70
	s_cselect_b32 s8, s67, s69
	s_add_i32 s74, 0, 0x14000
	s_waitcnt lgkmcnt(0)
	ds_read_b128 v[150:153], v154
	ds_read_b128 v[158:161], v154 offset:1024
	ds_read_b128 v[170:173], v154 offset:2048
	ds_read_b128 v[184:187], v154 offset:3072
	v_add_u32_e32 v154, s74, v1
	ds_read_b128 v[188:191], v154
	ds_read_b128 v[192:195], v154 offset:1024
	ds_read_b128 v[196:199], v154 offset:2048
	ds_read_b128 v[214:217], v154 offset:3072
	v_lshl_add_u64 v[154:155], s[86:87], 0, v[146:147]
	s_add_i32 m0, s17, 0xc000
	ds_read_b128 v[218:221], v156
	ds_read_b128 v[222:225], v156 offset:1024
	ds_read_b128 v[226:229], v156 offset:2048
	ds_read_b128 v[230:233], v156 offset:3072
	ds_read_b128 v[234:237], v156 offset:4096
	ds_read_b128 v[238:241], v156 offset:5120
	ds_read_b128 v[242:245], v156 offset:6144
	ds_read_b128 v[246:249], v156 offset:7168
	global_load_lds_dwordx4 v[154:155], off
	v_lshl_add_u64 v[154:155], s[86:87], 0, v[148:149]
	s_add_i32 m0, s17, 0xe000
	s_nop 0
	global_load_lds_dwordx4 v[154:155], off
	s_waitcnt vmcnt(8)
	s_waitcnt lgkmcnt(0)
	s_barrier
	s_setprio 1
	v_mfma_f32_16x16x32_bf16 v[132:135], v[150:153], v[218:221], v[132:135]
	v_mfma_f32_16x16x32_bf16 v[128:131], v[170:173], v[218:221], v[128:131]
	v_mfma_f32_16x16x32_bf16 v[124:127], v[150:153], v[226:229], v[124:127]
	v_mfma_f32_16x16x32_bf16 v[120:123], v[170:173], v[226:229], v[120:123]
	v_mfma_f32_16x16x32_bf16 v[106:109], v[150:153], v[234:237], v[106:109]
	v_mfma_f32_16x16x32_bf16 v[98:101], v[170:173], v[234:237], v[98:101]
	v_mfma_f32_16x16x32_bf16 v[90:93], v[150:153], v[242:245], v[90:93]
	v_mfma_f32_16x16x32_bf16 v[82:85], v[170:173], v[242:245], v[82:85]
	v_mfma_f32_16x16x32_bf16 v[132:135], v[158:161], v[222:225], v[132:135]
	v_mfma_f32_16x16x32_bf16 v[128:131], v[184:187], v[222:225], v[128:131]
	v_mfma_f32_16x16x32_bf16 v[124:127], v[158:161], v[230:233], v[124:127]
	v_mfma_f32_16x16x32_bf16 v[120:123], v[184:187], v[230:233], v[120:123]
	v_mfma_f32_16x16x32_bf16 v[106:109], v[158:161], v[238:241], v[106:109]
	v_mfma_f32_16x16x32_bf16 v[98:101], v[184:187], v[238:241], v[98:101]
	v_mfma_f32_16x16x32_bf16 v[90:93], v[158:161], v[246:249], v[90:93]
	v_mfma_f32_16x16x32_bf16 v[82:85], v[184:187], v[246:249], v[82:85]
	v_mfma_f32_16x16x32_bf16 v[116:119], v[188:191], v[218:221], v[116:119]
	v_mfma_f32_16x16x32_bf16 v[102:105], v[196:199], v[218:221], v[102:105]
	v_mfma_f32_16x16x32_bf16 v[94:97], v[188:191], v[226:229], v[94:97]
	v_mfma_f32_16x16x32_bf16 v[86:89], v[196:199], v[226:229], v[86:89]
	v_mfma_f32_16x16x32_bf16 v[78:81], v[188:191], v[234:237], v[78:81]
	v_mfma_f32_16x16x32_bf16 v[74:77], v[196:199], v[234:237], v[74:77]
	v_mfma_f32_16x16x32_bf16 v[70:73], v[188:191], v[242:245], v[70:73]
	v_mfma_f32_16x16x32_bf16 v[66:69], v[196:199], v[242:245], v[66:69]
	v_mfma_f32_16x16x32_bf16 v[116:119], v[192:195], v[222:225], v[116:119]
	v_mfma_f32_16x16x32_bf16 v[102:105], v[214:217], v[222:225], v[102:105]
	v_mfma_f32_16x16x32_bf16 v[94:97], v[192:195], v[230:233], v[94:97]
	v_mfma_f32_16x16x32_bf16 v[86:89], v[214:217], v[230:233], v[86:89]
	v_mfma_f32_16x16x32_bf16 v[78:81], v[192:195], v[238:241], v[78:81]
	v_mfma_f32_16x16x32_bf16 v[74:77], v[214:217], v[238:241], v[74:77]
	v_mfma_f32_16x16x32_bf16 v[70:73], v[192:195], v[246:249], v[70:73]
	v_mfma_f32_16x16x32_bf16 v[66:69], v[214:217], v[246:249], v[66:69]
	s_setprio 0
	s_barrier
	s_add_i32 s72, s73, s37
	v_lshl_add_u64 v[154:155], s[8:9], 0, v[136:137]
	s_mov_b32 m0, s72
	ds_read_b128 v[218:221], v156 offset:16384
	ds_read_b128 v[222:225], v156 offset:17408
	ds_read_b128 v[226:229], v156 offset:18432
	ds_read_b128 v[230:233], v156 offset:19456
	ds_read_b128 v[234:237], v156 offset:20480
	ds_read_b128 v[238:241], v156 offset:21504
	ds_read_b128 v[242:245], v156 offset:22528
	ds_read_b128 v[246:249], v156 offset:23552
	global_load_lds_dwordx4 v[154:155], off
	s_add_i32 m0, s72, 0x2000
	s_add_u32 s72, s8, 0x200000
	v_lshl_add_u64 v[162:163], s[8:9], 0, v[140:141]
	s_addc_u32 s73, s9, 0
	s_add_i32 s74, s74, s37
	global_load_lds_dwordx4 v[162:163], off
	v_lshl_add_u64 v[200:201], s[72:73], 0, v[136:137]
	s_mov_b32 m0, s74
	v_lshl_add_u64 v[206:207], s[92:93], 0, v[138:139]
	global_load_lds_dwordx4 v[200:201], off
	v_lshl_add_u64 v[200:201], s[72:73], 0, v[140:141]
	s_add_i32 m0, s74, 0x2000
	s_nop 0
	global_load_lds_dwordx4 v[200:201], off
	v_lshl_add_u64 v[200:201], s[92:93], 0, v[110:111]
	s_mov_b32 m0, s17
	s_nop 0
	global_load_lds_dwordx4 v[200:201], off
	s_mov_b32 m0, s57
	s_nop 0
	global_load_lds_dwordx4 v[206:207], off
	s_waitcnt vmcnt(8)
	s_waitcnt lgkmcnt(0)
	s_barrier
	s_setprio 1
	v_mfma_f32_16x16x32_bf16 v[62:65], v[150:153], v[218:221], v[62:65]
	v_mfma_f32_16x16x32_bf16 v[58:61], v[170:173], v[218:221], v[58:61]
	v_mfma_f32_16x16x32_bf16 v[54:57], v[150:153], v[226:229], v[54:57]
	v_mfma_f32_16x16x32_bf16 v[50:53], v[170:173], v[226:229], v[50:53]
	v_mfma_f32_16x16x32_bf16 v[42:45], v[150:153], v[234:237], v[42:45]
	v_mfma_f32_16x16x32_bf16 v[34:37], v[170:173], v[234:237], v[34:37]
	v_mfma_f32_16x16x32_bf16 v[26:29], v[150:153], v[242:245], v[26:29]
	v_mfma_f32_16x16x32_bf16 v[18:21], v[170:173], v[242:245], v[18:21]
	v_mfma_f32_16x16x32_bf16 v[62:65], v[158:161], v[222:225], v[62:65]
	v_mfma_f32_16x16x32_bf16 v[58:61], v[184:187], v[222:225], v[58:61]
	v_mfma_f32_16x16x32_bf16 v[54:57], v[158:161], v[230:233], v[54:57]
	v_mfma_f32_16x16x32_bf16 v[50:53], v[184:187], v[230:233], v[50:53]
	v_mfma_f32_16x16x32_bf16 v[42:45], v[158:161], v[238:241], v[42:45]
	v_mfma_f32_16x16x32_bf16 v[34:37], v[184:187], v[238:241], v[34:37]
	v_mfma_f32_16x16x32_bf16 v[26:29], v[158:161], v[246:249], v[26:29]
	v_mfma_f32_16x16x32_bf16 v[18:21], v[184:187], v[246:249], v[18:21]
	v_mfma_f32_16x16x32_bf16 v[46:49], v[188:191], v[218:221], v[46:49]
	v_mfma_f32_16x16x32_bf16 v[38:41], v[196:199], v[218:221], v[38:41]
	v_mfma_f32_16x16x32_bf16 v[30:33], v[188:191], v[226:229], v[30:33]
	v_mfma_f32_16x16x32_bf16 v[22:25], v[196:199], v[226:229], v[22:25]
	v_mfma_f32_16x16x32_bf16 v[14:17], v[188:191], v[234:237], v[14:17]
	v_mfma_f32_16x16x32_bf16 v[10:13], v[196:199], v[234:237], v[10:13]
	v_mfma_f32_16x16x32_bf16 v[6:9], v[188:191], v[242:245], v[6:9]
	v_mfma_f32_16x16x32_bf16 v[2:5], v[196:199], v[242:245], v[2:5]
	v_mfma_f32_16x16x32_bf16 v[46:49], v[192:195], v[222:225], v[46:49]
	v_mfma_f32_16x16x32_bf16 v[38:41], v[214:217], v[222:225], v[38:41]
	v_mfma_f32_16x16x32_bf16 v[30:33], v[192:195], v[230:233], v[30:33]
	v_mfma_f32_16x16x32_bf16 v[22:25], v[214:217], v[230:233], v[22:25]
	v_mfma_f32_16x16x32_bf16 v[14:17], v[192:195], v[238:241], v[14:17]
	v_mfma_f32_16x16x32_bf16 v[10:13], v[214:217], v[238:241], v[10:13]
	v_mfma_f32_16x16x32_bf16 v[6:9], v[192:195], v[246:249], v[6:9]
	v_mfma_f32_16x16x32_bf16 v[2:5], v[214:217], v[246:249], v[2:5]
	s_setprio 0
	s_barrier
	s_add_i32 s74, 0, 0x18000
	v_add_u32_e32 v157, s74, v1
	s_add_i32 s75, 0, 0x1c000
	ds_read_b128 v[150:153], v157
	ds_read_b128 v[158:161], v157 offset:1024
	ds_read_b128 v[170:173], v157 offset:2048
	ds_read_b128 v[184:187], v157 offset:3072
	v_add_u32_e32 v157, s75, v1
	ds_read_b128 v[188:191], v157
	ds_read_b128 v[192:195], v157 offset:1024
	ds_read_b128 v[196:199], v157 offset:2048
	ds_read_b128 v[214:217], v157 offset:3072
	s_add_u32 s72, s92, 0x200000
	s_addc_u32 s73, s93, 0
	s_mov_b32 m0, s58
	v_lshl_add_u64 v[250:251], s[72:73], 0, v[110:111]
	ds_read_b128 v[218:221], v156 offset:32768
	ds_read_b128 v[222:225], v156 offset:33792
	ds_read_b128 v[226:229], v156 offset:34816
	ds_read_b128 v[230:233], v156 offset:35840
	ds_read_b128 v[234:237], v156 offset:36864
	ds_read_b128 v[238:241], v156 offset:37888
	ds_read_b128 v[242:245], v156 offset:38912
	ds_read_b128 v[246:249], v156 offset:39936
	global_load_lds_dwordx4 v[250:251], off
	v_lshl_add_u64 v[250:251], s[72:73], 0, v[138:139]
	s_mov_b32 m0, s59
	s_nop 0
	global_load_lds_dwordx4 v[250:251], off
	s_waitcnt vmcnt(8)
	s_waitcnt lgkmcnt(0)
	s_barrier
	s_setprio 1
	v_mfma_f32_16x16x32_bf16 v[132:135], v[150:153], v[218:221], v[132:135]
	v_mfma_f32_16x16x32_bf16 v[128:131], v[170:173], v[218:221], v[128:131]
	v_mfma_f32_16x16x32_bf16 v[124:127], v[150:153], v[226:229], v[124:127]
	v_mfma_f32_16x16x32_bf16 v[120:123], v[170:173], v[226:229], v[120:123]
	v_mfma_f32_16x16x32_bf16 v[106:109], v[150:153], v[234:237], v[106:109]
	v_mfma_f32_16x16x32_bf16 v[98:101], v[170:173], v[234:237], v[98:101]
	v_mfma_f32_16x16x32_bf16 v[90:93], v[150:153], v[242:245], v[90:93]
	v_mfma_f32_16x16x32_bf16 v[82:85], v[170:173], v[242:245], v[82:85]
	v_mfma_f32_16x16x32_bf16 v[132:135], v[158:161], v[222:225], v[132:135]
	v_mfma_f32_16x16x32_bf16 v[128:131], v[184:187], v[222:225], v[128:131]
	v_mfma_f32_16x16x32_bf16 v[124:127], v[158:161], v[230:233], v[124:127]
	v_mfma_f32_16x16x32_bf16 v[120:123], v[184:187], v[230:233], v[120:123]
	v_mfma_f32_16x16x32_bf16 v[106:109], v[158:161], v[238:241], v[106:109]
	v_mfma_f32_16x16x32_bf16 v[98:101], v[184:187], v[238:241], v[98:101]
	v_mfma_f32_16x16x32_bf16 v[90:93], v[158:161], v[246:249], v[90:93]
	v_mfma_f32_16x16x32_bf16 v[82:85], v[184:187], v[246:249], v[82:85]
	v_mfma_f32_16x16x32_bf16 v[116:119], v[188:191], v[218:221], v[116:119]
	v_mfma_f32_16x16x32_bf16 v[102:105], v[196:199], v[218:221], v[102:105]
	v_mfma_f32_16x16x32_bf16 v[94:97], v[188:191], v[226:229], v[94:97]
	v_mfma_f32_16x16x32_bf16 v[86:89], v[196:199], v[226:229], v[86:89]
	v_mfma_f32_16x16x32_bf16 v[78:81], v[188:191], v[234:237], v[78:81]
	v_mfma_f32_16x16x32_bf16 v[74:77], v[196:199], v[234:237], v[74:77]
	v_mfma_f32_16x16x32_bf16 v[70:73], v[188:191], v[242:245], v[70:73]
	v_mfma_f32_16x16x32_bf16 v[66:69], v[196:199], v[242:245], v[66:69]
	v_mfma_f32_16x16x32_bf16 v[116:119], v[192:195], v[222:225], v[116:119]
	v_mfma_f32_16x16x32_bf16 v[102:105], v[214:217], v[222:225], v[102:105]
	v_mfma_f32_16x16x32_bf16 v[94:97], v[192:195], v[230:233], v[94:97]
	v_mfma_f32_16x16x32_bf16 v[86:89], v[214:217], v[230:233], v[86:89]
	v_mfma_f32_16x16x32_bf16 v[78:81], v[192:195], v[238:241], v[78:81]
	v_mfma_f32_16x16x32_bf16 v[74:77], v[214:217], v[238:241], v[74:77]
	v_mfma_f32_16x16x32_bf16 v[70:73], v[192:195], v[246:249], v[70:73]
	v_mfma_f32_16x16x32_bf16 v[66:69], v[214:217], v[246:249], v[66:69]
	s_setprio 0
	s_barrier
	s_add_i32 s72, s74, s37
	v_lshl_add_u64 v[154:155], v[154:155], 0, s[26:27]
	s_mov_b32 m0, s72
	ds_read_b128 v[218:221], v156 offset:49152
	ds_read_b128 v[222:225], v156 offset:50176
	ds_read_b128 v[226:229], v156 offset:51200
	ds_read_b128 v[230:233], v156 offset:52224
	ds_read_b128 v[234:237], v156 offset:53248
	ds_read_b128 v[238:241], v156 offset:54272
	ds_read_b128 v[242:245], v156 offset:55296
	ds_read_b128 v[246:249], v156 offset:56320
	global_load_lds_dwordx4 v[154:155], off
	s_add_i32 m0, s72, 0x2000
	s_add_u32 s8, s8, 0x200080
	v_lshl_add_u64 v[154:155], v[162:163], 0, s[26:27]
	s_addc_u32 s9, s9, 0
	s_add_i32 s72, s75, s37
	global_load_lds_dwordx4 v[154:155], off
	v_lshl_add_u64 v[154:155], s[8:9], 0, v[136:137]
	s_mov_b32 m0, s72
	s_nop 0
	global_load_lds_dwordx4 v[154:155], off
	v_lshl_add_u64 v[154:155], s[8:9], 0, v[140:141]
	s_add_i32 m0, s72, 0x2000
	s_nop 0
	global_load_lds_dwordx4 v[154:155], off
	v_lshl_add_u64 v[154:155], v[200:201], 0, s[26:27]
	s_mov_b32 m0, s61
	s_nop 0
	global_load_lds_dwordx4 v[154:155], off
	v_lshl_add_u64 v[154:155], v[206:207], 0, s[26:27]
	s_mov_b32 m0, s62
	s_nop 0
	global_load_lds_dwordx4 v[154:155], off
	s_waitcnt vmcnt(8)
	s_waitcnt lgkmcnt(0)
	s_barrier
	s_setprio 1
	v_mfma_f32_16x16x32_bf16 v[62:65], v[150:153], v[218:221], v[62:65]
	v_mfma_f32_16x16x32_bf16 v[58:61], v[170:173], v[218:221], v[58:61]
	v_mfma_f32_16x16x32_bf16 v[54:57], v[150:153], v[226:229], v[54:57]
	v_mfma_f32_16x16x32_bf16 v[50:53], v[170:173], v[226:229], v[50:53]
	v_mfma_f32_16x16x32_bf16 v[42:45], v[150:153], v[234:237], v[42:45]
	v_mfma_f32_16x16x32_bf16 v[34:37], v[170:173], v[234:237], v[34:37]
	v_mfma_f32_16x16x32_bf16 v[26:29], v[150:153], v[242:245], v[26:29]
	v_mfma_f32_16x16x32_bf16 v[18:21], v[170:173], v[242:245], v[18:21]
	v_mfma_f32_16x16x32_bf16 v[62:65], v[158:161], v[222:225], v[62:65]
	v_mfma_f32_16x16x32_bf16 v[58:61], v[184:187], v[222:225], v[58:61]
	v_mfma_f32_16x16x32_bf16 v[54:57], v[158:161], v[230:233], v[54:57]
	v_mfma_f32_16x16x32_bf16 v[50:53], v[184:187], v[230:233], v[50:53]
	v_mfma_f32_16x16x32_bf16 v[42:45], v[158:161], v[238:241], v[42:45]
	v_mfma_f32_16x16x32_bf16 v[34:37], v[184:187], v[238:241], v[34:37]
	v_mfma_f32_16x16x32_bf16 v[26:29], v[158:161], v[246:249], v[26:29]
	v_mfma_f32_16x16x32_bf16 v[18:21], v[184:187], v[246:249], v[18:21]
	v_mfma_f32_16x16x32_bf16 v[46:49], v[188:191], v[218:221], v[46:49]
	v_mfma_f32_16x16x32_bf16 v[38:41], v[196:199], v[218:221], v[38:41]
	v_mfma_f32_16x16x32_bf16 v[30:33], v[188:191], v[226:229], v[30:33]
	v_mfma_f32_16x16x32_bf16 v[22:25], v[196:199], v[226:229], v[22:25]
	v_mfma_f32_16x16x32_bf16 v[14:17], v[188:191], v[234:237], v[14:17]
	v_mfma_f32_16x16x32_bf16 v[10:13], v[196:199], v[234:237], v[10:13]
	v_mfma_f32_16x16x32_bf16 v[6:9], v[188:191], v[242:245], v[6:9]
	v_mfma_f32_16x16x32_bf16 v[2:5], v[196:199], v[242:245], v[2:5]
	v_mfma_f32_16x16x32_bf16 v[46:49], v[192:195], v[222:225], v[46:49]
	v_mfma_f32_16x16x32_bf16 v[38:41], v[214:217], v[222:225], v[38:41]
	v_mfma_f32_16x16x32_bf16 v[30:33], v[192:195], v[230:233], v[30:33]
	v_mfma_f32_16x16x32_bf16 v[22:25], v[214:217], v[230:233], v[22:25]
	v_mfma_f32_16x16x32_bf16 v[14:17], v[192:195], v[238:241], v[14:17]
	v_mfma_f32_16x16x32_bf16 v[10:13], v[214:217], v[238:241], v[10:13]
	v_mfma_f32_16x16x32_bf16 v[6:9], v[192:195], v[246:249], v[6:9]
	v_mfma_f32_16x16x32_bf16 v[2:5], v[214:217], v[246:249], v[2:5]
	s_setprio 0
	s_barrier
	s_add_u32 s86, s86, 0x100
	s_addc_u32 s87, s87, 0
	s_add_u32 s69, s69, 0x100
	s_addc_u32 s70, s70, 0
	s_cmp_ge_u32 s71, s66
	s_mov_b32 s8, s71
	s_cbranch_scc0 .LBB0_853
	s_and_b64 vcc, exec, s[42:43]
	s_cbranch_vccz .LBB0_856
	s_barrier
